# removed compiler vmcnt(0) flush at GEMM unit start (preheader flush), stores/prefetch stay in flight
# speedup vs baseline: 1.0045x; 1.0045x over previous
; template <class Epi>
; __device__ __forceinline__ void gemm_phase(LAS unsigned char* lds, const Gemm g, const StaticOrder& S, const Epi& E, const bool perm) {
;     ...
; #pragma unroll
;         for (int a = 0; a < 2; ++a)
; #pragma unroll
;             for (int b = 0; b < 2; ++b)
; #pragma unroll
;                 for (int m = 0; m < 4; ++m)
; #pragma unroll
;                     for (int n = 0; n < 2; ++n) acc[a][b][m][n] = (f32x4){0.f, 0.f, 0.f, 0.f};
;         cur = nxt; cA = nA; cB = nB; ++ui;
.LBB0_461:
	s_lshl_b32 s51, s70, 8
	s_add_u32 s6, s6, 0x80
	s_addc_u32 s7, s7, 0
	s_add_u32 s55, s22, 0x100
	v_mov_b32_e32 v0, 0
	v_lshl_add_u32 v218, s46, 8, v244
	v_or_b32_e32 v220, s51, v246
	s_addc_u32 s78, s23, 0
	s_mov_b32 s79, 0
	s_mov_b32 s60, 0
	v_mov_b32_e32 v1, v0
	v_mov_b32_e32 v2, v0
	v_mov_b32_e32 v3, v0
	v_mov_b32_e32 v4, v0
	v_mov_b32_e32 v5, v0
	v_mov_b32_e32 v6, v0
	v_mov_b32_e32 v7, v0
	v_mov_b32_e32 v16, v0
	v_mov_b32_e32 v17, v0
	v_mov_b32_e32 v18, v0
	v_mov_b32_e32 v19, v0
	v_mov_b32_e32 v20, v0
	v_mov_b32_e32 v21, v0
	v_mov_b32_e32 v22, v0
	v_mov_b32_e32 v23, v0
	v_mov_b32_e32 v32, v0
	v_mov_b32_e32 v33, v0
	v_mov_b32_e32 v34, v0
	v_mov_b32_e32 v35, v0
	v_mov_b32_e32 v36, v0
	v_mov_b32_e32 v37, v0
	v_mov_b32_e32 v38, v0
	v_mov_b32_e32 v39, v0
	v_mov_b32_e32 v48, v0
	v_mov_b32_e32 v49, v0
	v_mov_b32_e32 v50, v0
	v_mov_b32_e32 v51, v0
	v_mov_b32_e32 v52, v0
	v_mov_b32_e32 v53, v0
	v_mov_b32_e32 v54, v0
	v_mov_b32_e32 v55, v0
	v_mov_b32_e32 v8, v0
	v_mov_b32_e32 v9, v0
	v_mov_b32_e32 v10, v0
	v_mov_b32_e32 v11, v0
	v_mov_b32_e32 v12, v0
	v_mov_b32_e32 v13, v0
	v_mov_b32_e32 v14, v0
	v_mov_b32_e32 v15, v0
	v_mov_b32_e32 v24, v0
	v_mov_b32_e32 v25, v0
	v_mov_b32_e32 v26, v0
	v_mov_b32_e32 v27, v0
	v_mov_b32_e32 v28, v0
	v_mov_b32_e32 v29, v0
	v_mov_b32_e32 v30, v0
	v_mov_b32_e32 v31, v0
	v_mov_b32_e32 v40, v0
	v_mov_b32_e32 v41, v0
	v_mov_b32_e32 v42, v0
	v_mov_b32_e32 v43, v0
	v_mov_b32_e32 v44, v0
	v_mov_b32_e32 v45, v0
	v_mov_b32_e32 v46, v0
	v_mov_b32_e32 v47, v0
	v_mov_b32_e32 v56, v0
	v_mov_b32_e32 v57, v0
	v_mov_b32_e32 v58, v0
	v_mov_b32_e32 v59, v0
	v_mov_b32_e32 v60, v0
	v_mov_b32_e32 v61, v0
	v_mov_b32_e32 v62, v0
	v_mov_b32_e32 v63, v0
	v_mov_b32_e32 v64, v0
	v_mov_b32_e32 v65, v0
	v_mov_b32_e32 v66, v0
	v_mov_b32_e32 v67, v0
	v_mov_b32_e32 v68, v0
	v_mov_b32_e32 v69, v0
	v_mov_b32_e32 v70, v0
	v_mov_b32_e32 v71, v0
	v_mov_b32_e32 v80, v0
	v_mov_b32_e32 v81, v0
	v_mov_b32_e32 v82, v0
	v_mov_b32_e32 v83, v0
	v_mov_b32_e32 v84, v0
	v_mov_b32_e32 v85, v0
	v_mov_b32_e32 v86, v0
	v_mov_b32_e32 v87, v0
	v_mov_b32_e32 v96, v0
	v_mov_b32_e32 v97, v0
	v_mov_b32_e32 v98, v0
	v_mov_b32_e32 v99, v0
	v_mov_b32_e32 v100, v0
	v_mov_b32_e32 v101, v0
	v_mov_b32_e32 v102, v0
	v_mov_b32_e32 v103, v0
	v_mov_b32_e32 v112, v0
	v_mov_b32_e32 v113, v0
	v_mov_b32_e32 v114, v0
	v_mov_b32_e32 v115, v0
	v_mov_b32_e32 v116, v0
	v_mov_b32_e32 v117, v0
	v_mov_b32_e32 v118, v0
	v_mov_b32_e32 v119, v0
	v_mov_b32_e32 v72, v0
	v_mov_b32_e32 v73, v0
	v_mov_b32_e32 v74, v0
	v_mov_b32_e32 v75, v0
	v_mov_b32_e32 v76, v0
	v_mov_b32_e32 v77, v0
	v_mov_b32_e32 v78, v0
	v_mov_b32_e32 v79, v0
	v_mov_b32_e32 v88, v0
	v_mov_b32_e32 v89, v0
	v_mov_b32_e32 v90, v0
	v_mov_b32_e32 v91, v0
	v_mov_b32_e32 v92, v0
	v_mov_b32_e32 v93, v0
	v_mov_b32_e32 v94, v0
	v_mov_b32_e32 v95, v0
	v_mov_b32_e32 v104, v0
	v_mov_b32_e32 v105, v0
	v_mov_b32_e32 v106, v0
	v_mov_b32_e32 v107, v0
	v_mov_b32_e32 v108, v0
	v_mov_b32_e32 v109, v0
	v_mov_b32_e32 v110, v0
	v_mov_b32_e32 v111, v0
	v_mov_b32_e32 v120, v0
	v_mov_b32_e32 v121, v0
	v_mov_b32_e32 v122, v0
	v_mov_b32_e32 v123, v0
	v_mov_b32_e32 v124, v0
	v_mov_b32_e32 v125, v0
	v_mov_b32_e32 v126, v0
	v_mov_b32_e32 v127, v0
	s_branch .LBB0_463
